# memKV GEMM (P0b): remaining per-segment s_setprio toggles deleted (A/B of the last flips)
# baseline (speedup 1.0000x reference)
; #define PG8_STAGE(bufoff, gbase, voff) do { _Pragma("unroll") for (int _i = 0; _i < 2; ++_i) \
;         __builtin_amdgcn_global_load_lds((const unsigned*)((const char*)(gbase) + (voff)[_i]), (PG8_LAS unsigned*)(lds + (bufoff) + ldsw + _i * 8192), 16, 0, 0); } while (0)
; #define PG8_LDA(dst, b, h) do { _Pragma("unroll") for (int m = 0; m < 4; ++m) _Pragma("unroll") for (int k = 0; k < 2; ++k) dst[m][k] = *(const PG8_LAS bf16x8*)(lds + PG8_SA(b, h) + aoff + m * 2048 + k * 1024); } while (0)
; #define PG8_LDB(dst, b, h) do { _Pragma("unroll") for (int n = 0; n < 2; ++n) _Pragma("unroll") for (int k = 0; k < 2; ++k) dst[n][k] = *(const PG8_LAS bf16x8*)(lds + PG8_SB(b, h) + boff + n * 2048 + k * 1024); } while (0)
; #define PG8_MMA(ai, bj, At, Bt) do { __builtin_amdgcn_s_setprio(1); _Pragma("unroll") for (int m = 0; m < 4; ++m) _Pragma("unroll") for (int n = 0; n < 2; ++n) _Pragma("unroll") for (int k = 0; k < 2; ++k) \
;         acc[ai][bj][m][n] = __builtin_amdgcn_mfma_f32_16x16x32_bf16(Bt[n][k], At[m][k], acc[ai][bj][m][n], 0, 0, 0); __builtin_amdgcn_s_setprio(0); } while (0)
; #define PG8_WAIT_V(n) asm volatile("s_waitcnt vmcnt(" #n ")" ::: "memory")
; #define PG8_WAIT_L(n) asm volatile("s_waitcnt lgkmcnt(" #n ")" ::: "memory")
; #define PG8_BAR __builtin_amdgcn_s_barrier()
; #define PG8_SCHED __builtin_amdgcn_sched_barrier(0)
; template <class Epi, class Sched, bool ALIGN_EPI = false, bool SP2 = false>
; __device__ __forceinline__ void gemm_phase(PG8_LAS unsigned char* lds, const Gemm g, const Sched& S, const Epi& E) {
;     ...
;             PG8_LDB(B0, 0, 0); PG8_LDB(B1, 0, 1); PG8_SCHED; PG8_LDA(At, 0, 0); PG8_STAGE(PG8_SA(1, 1), a1 + hstep, voffA);
;             PG8_WAIT_V(8); PG8_WAIT_L(0); PG8_BAR; PG8_MMA(0, 0, At, B0); PG8_MMA(0, 1, At, B1); PG8_BAR; PG8_SCHED;
;             PG8_LDA(At, 0, 1); PG8_STAGE(PG8_SB(0, 0), b2, voffB); PG8_STAGE(PG8_SB(0, 1), b2 + hstep, voffB); PG8_STAGE(PG8_SA(0, 0), a2, voffA);
;             PG8_WAIT_V(8); PG8_WAIT_L(0); PG8_BAR; PG8_MMA(1, 0, At, B0); PG8_MMA(1, 1, At, B1); PG8_BAR; PG8_SCHED;
.LBB0_349:
	ds_read_b128 v[142:145], v148
	ds_read_b128 v[152:155], v148 offset:1024
	ds_read_b128 v[156:159], v148 offset:2048
	ds_read_b128 v[160:163], v148 offset:3072
	ds_read_b128 v[164:167], v149
	ds_read_b128 v[168:171], v149 offset:1024
	ds_read_b128 v[172:175], v149 offset:2048
	ds_read_b128 v[176:179], v149 offset:3072
	s_add_u32 s2, s22, 0xfffc0080
	s_addc_u32 s3, s23, -1
	s_cmp_eq_u32 s55, 12
	s_cselect_b32 s25, s15, s3
	s_cselect_b32 s24, s47, s2
	s_cselect_b32 s3, s13, s54
	s_cselect_b32 s2, s48, s49
	v_lshl_add_u64 v[214:215], s[22:23], 0, v[138:139]
	s_add_i32 m0, s21, 0xc000
	ds_read_b128 v[180:183], v150
	ds_read_b128 v[184:187], v150 offset:1024
	ds_read_b128 v[188:191], v150 offset:2048
	ds_read_b128 v[192:195], v150 offset:3072
	ds_read_b128 v[196:199], v150 offset:4096
	ds_read_b128 v[200:203], v150 offset:5120
	ds_read_b128 v[206:209], v150 offset:6144
	ds_read_b128 v[210:213], v150 offset:7168
	global_load_lds_dwordx4 v[214:215], off
	v_lshl_add_u64 v[214:215], s[22:23], 0, v[140:141]
	s_add_i32 m0, s21, 0xe000
	s_nop 0
	global_load_lds_dwordx4 v[214:215], off
	s_waitcnt vmcnt(8)
	s_waitcnt lgkmcnt(0)
	s_barrier
	s_waitcnt lgkmcnt(0)
	v_mfma_f32_16x16x32_bf16 v[124:127], v[142:145], v[180:183], v[124:127]
	v_mfma_f32_16x16x32_bf16 v[120:123], v[156:159], v[180:183], v[120:123]
	v_mfma_f32_16x16x32_bf16 v[108:111], v[142:145], v[188:191], v[108:111]
	v_mfma_f32_16x16x32_bf16 v[104:107], v[156:159], v[188:191], v[104:107]
	v_mfma_f32_16x16x32_bf16 v[92:95], v[142:145], v[196:199], v[92:95]
	v_mfma_f32_16x16x32_bf16 v[88:91], v[156:159], v[196:199], v[88:91]
	v_mfma_f32_16x16x32_bf16 v[76:79], v[142:145], v[206:209], v[76:79]
	v_mfma_f32_16x16x32_bf16 v[72:75], v[156:159], v[206:209], v[72:75]
	v_mfma_f32_16x16x32_bf16 v[124:127], v[152:155], v[184:187], v[124:127]
	v_mfma_f32_16x16x32_bf16 v[120:123], v[160:163], v[184:187], v[120:123]
	v_mfma_f32_16x16x32_bf16 v[108:111], v[152:155], v[192:195], v[108:111]
	v_mfma_f32_16x16x32_bf16 v[104:107], v[160:163], v[192:195], v[104:107]
	v_mfma_f32_16x16x32_bf16 v[92:95], v[152:155], v[200:203], v[92:95]
	v_mfma_f32_16x16x32_bf16 v[88:91], v[160:163], v[200:203], v[88:91]
	v_mfma_f32_16x16x32_bf16 v[76:79], v[152:155], v[210:213], v[76:79]
	v_mfma_f32_16x16x32_bf16 v[72:75], v[160:163], v[210:213], v[72:75]
	v_mfma_f32_16x16x32_bf16 v[116:119], v[164:167], v[180:183], v[116:119]
	v_mfma_f32_16x16x32_bf16 v[112:115], v[172:175], v[180:183], v[112:115]
	v_mfma_f32_16x16x32_bf16 v[100:103], v[164:167], v[188:191], v[100:103]
	v_mfma_f32_16x16x32_bf16 v[96:99], v[172:175], v[188:191], v[96:99]
	v_mfma_f32_16x16x32_bf16 v[84:87], v[164:167], v[196:199], v[84:87]
	v_mfma_f32_16x16x32_bf16 v[80:83], v[172:175], v[196:199], v[80:83]
	v_mfma_f32_16x16x32_bf16 v[68:71], v[164:167], v[206:209], v[68:71]
	v_mfma_f32_16x16x32_bf16 v[64:67], v[172:175], v[206:209], v[64:67]
	v_mfma_f32_16x16x32_bf16 v[116:119], v[168:171], v[184:187], v[116:119]
	v_mfma_f32_16x16x32_bf16 v[112:115], v[176:179], v[184:187], v[112:115]
	v_mfma_f32_16x16x32_bf16 v[100:103], v[168:171], v[192:195], v[100:103]
	v_mfma_f32_16x16x32_bf16 v[96:99], v[176:179], v[192:195], v[96:99]
	v_mfma_f32_16x16x32_bf16 v[84:87], v[168:171], v[200:203], v[84:87]
	v_mfma_f32_16x16x32_bf16 v[80:83], v[176:179], v[200:203], v[80:83]
	v_mfma_f32_16x16x32_bf16 v[68:71], v[168:171], v[210:213], v[68:71]
	v_mfma_f32_16x16x32_bf16 v[64:67], v[176:179], v[210:213], v[64:67]
	s_barrier
	s_add_i32 s58, s43, s31
	v_lshl_add_u64 v[214:215], s[2:3], 0, v[130:131]
	s_mov_b32 m0, s58
	ds_read_b128 v[180:183], v150 offset:16384
	ds_read_b128 v[184:187], v150 offset:17408
	ds_read_b128 v[188:191], v150 offset:18432
	ds_read_b128 v[192:195], v150 offset:19456
	ds_read_b128 v[196:199], v150 offset:20480
	ds_read_b128 v[200:203], v150 offset:21504
	ds_read_b128 v[206:209], v150 offset:22528
	ds_read_b128 v[210:213], v150 offset:23552
	global_load_lds_dwordx4 v[214:215], off
	s_add_i32 m0, s58, 0x2000
	s_add_u32 s58, s2, 0x40000
	v_lshl_add_u64 v[216:217], s[2:3], 0, v[134:135]
	s_addc_u32 s59, s3, 0
	s_add_i32 s60, s44, s31
	global_load_lds_dwordx4 v[216:217], off
	v_lshl_add_u64 v[218:219], s[58:59], 0, v[130:131]
	s_mov_b32 m0, s60
	v_lshl_add_u64 v[220:221], s[24:25], 0, v[132:133]
	global_load_lds_dwordx4 v[218:219], off
	v_lshl_add_u64 v[218:219], s[58:59], 0, v[134:135]
	s_add_i32 m0, s60, 0x2000
	s_nop 0
	global_load_lds_dwordx4 v[218:219], off
	v_lshl_add_u64 v[218:219], s[24:25], 0, v[128:129]
	s_mov_b32 m0, s21
	s_nop 0
	global_load_lds_dwordx4 v[218:219], off
	s_mov_b32 m0, s35
	s_nop 0
	global_load_lds_dwordx4 v[220:221], off
	s_waitcnt vmcnt(8)
	s_waitcnt lgkmcnt(0)
	s_barrier
; #define PG8_STAGE(bufoff, gbase, voff) do { _Pragma("unroll") for (int _i = 0; _i < 2; ++_i) \
;         __builtin_amdgcn_global_load_lds((const unsigned*)((const char*)(gbase) + (voff)[_i]), (PG8_LAS unsigned*)(lds + (bufoff) + ldsw + _i * 8192), 16, 0, 0); } while (0)
; #define PG8_LDA(dst, b, h) do { _Pragma("unroll") for (int m = 0; m < 4; ++m) _Pragma("unroll") for (int k = 0; k < 2; ++k) dst[m][k] = *(const PG8_LAS bf16x8*)(lds + PG8_SA(b, h) + aoff + m * 2048 + k * 1024); } while (0)
; #define PG8_LDB(dst, b, h) do { _Pragma("unroll") for (int n = 0; n < 2; ++n) _Pragma("unroll") for (int k = 0; k < 2; ++k) dst[n][k] = *(const PG8_LAS bf16x8*)(lds + PG8_SB(b, h) + boff + n * 2048 + k * 1024); } while (0)
; #define PG8_MMA(ai, bj, At, Bt) do { __builtin_amdgcn_s_setprio(1); _Pragma("unroll") for (int m = 0; m < 4; ++m) _Pragma("unroll") for (int n = 0; n < 2; ++n) _Pragma("unroll") for (int k = 0; k < 2; ++k) \
;         acc[ai][bj][m][n] = __builtin_amdgcn_mfma_f32_16x16x32_bf16(Bt[n][k], At[m][k], acc[ai][bj][m][n], 0, 0, 0); __builtin_amdgcn_s_setprio(0); } while (0)
; #define PG8_WAIT_V(n) asm volatile("s_waitcnt vmcnt(" #n ")" ::: "memory")
; #define PG8_WAIT_L(n) asm volatile("s_waitcnt lgkmcnt(" #n ")" ::: "memory")
; #define PG8_BAR __builtin_amdgcn_s_barrier()
; #define PG8_SCHED __builtin_amdgcn_sched_barrier(0)
; template <class Epi, class Sched, bool ALIGN_EPI = false, bool SP2 = false>
; __device__ __forceinline__ void gemm_phase(PG8_LAS unsigned char* lds, const Gemm g, const Sched& S, const Epi& E) {
;     ...
;             PG8_WAIT_V(8); PG8_WAIT_L(0); PG8_BAR; PG8_MMA(1, 0, At, B0); PG8_MMA(1, 1, At, B1); PG8_BAR; PG8_SCHED;
;             PG8_LDB(B0, 1, 0); PG8_LDB(B1, 1, 1); PG8_SCHED; PG8_LDA(At, 1, 0); PG8_STAGE(PG8_SA(0, 1), a2 + hstep, voffA);
;             PG8_WAIT_V(8); PG8_WAIT_L(0); PG8_BAR; PG8_MMA(0, 0, At, B0); PG8_MMA(0, 1, At, B1); PG8_BAR; PG8_SCHED;
	s_waitcnt lgkmcnt(0)
	v_mfma_f32_16x16x32_bf16 v[60:63], v[142:145], v[180:183], v[60:63]
	v_mfma_f32_16x16x32_bf16 v[56:59], v[156:159], v[180:183], v[56:59]
	v_mfma_f32_16x16x32_bf16 v[44:47], v[142:145], v[188:191], v[44:47]
	v_mfma_f32_16x16x32_bf16 v[40:43], v[156:159], v[188:191], v[40:43]
	v_mfma_f32_16x16x32_bf16 v[28:31], v[142:145], v[196:199], v[28:31]
	v_mfma_f32_16x16x32_bf16 v[24:27], v[156:159], v[196:199], v[24:27]
	v_mfma_f32_16x16x32_bf16 v[12:15], v[142:145], v[206:209], v[12:15]
	v_mfma_f32_16x16x32_bf16 v[8:11], v[156:159], v[206:209], v[8:11]
	v_mfma_f32_16x16x32_bf16 v[60:63], v[152:155], v[184:187], v[60:63]
	v_mfma_f32_16x16x32_bf16 v[56:59], v[160:163], v[184:187], v[56:59]
	v_mfma_f32_16x16x32_bf16 v[44:47], v[152:155], v[192:195], v[44:47]
	v_mfma_f32_16x16x32_bf16 v[40:43], v[160:163], v[192:195], v[40:43]
	v_mfma_f32_16x16x32_bf16 v[28:31], v[152:155], v[200:203], v[28:31]
	v_mfma_f32_16x16x32_bf16 v[24:27], v[160:163], v[200:203], v[24:27]
	v_mfma_f32_16x16x32_bf16 v[12:15], v[152:155], v[210:213], v[12:15]
	v_mfma_f32_16x16x32_bf16 v[8:11], v[160:163], v[210:213], v[8:11]
	v_mfma_f32_16x16x32_bf16 v[52:55], v[164:167], v[180:183], v[52:55]
	v_mfma_f32_16x16x32_bf16 v[48:51], v[172:175], v[180:183], v[48:51]
	v_mfma_f32_16x16x32_bf16 v[36:39], v[164:167], v[188:191], v[36:39]
	v_mfma_f32_16x16x32_bf16 v[32:35], v[172:175], v[188:191], v[32:35]
	v_mfma_f32_16x16x32_bf16 v[20:23], v[164:167], v[196:199], v[20:23]
	v_mfma_f32_16x16x32_bf16 v[16:19], v[172:175], v[196:199], v[16:19]
	v_mfma_f32_16x16x32_bf16 v[4:7], v[164:167], v[206:209], v[4:7]
	v_mfma_f32_16x16x32_bf16 v[0:3], v[172:175], v[206:209], v[0:3]
	v_mfma_f32_16x16x32_bf16 v[52:55], v[168:171], v[184:187], v[52:55]
	v_mfma_f32_16x16x32_bf16 v[48:51], v[176:179], v[184:187], v[48:51]
	v_mfma_f32_16x16x32_bf16 v[36:39], v[168:171], v[192:195], v[36:39]
	v_mfma_f32_16x16x32_bf16 v[32:35], v[176:179], v[192:195], v[32:35]
	v_mfma_f32_16x16x32_bf16 v[20:23], v[168:171], v[200:203], v[20:23]
	v_mfma_f32_16x16x32_bf16 v[16:19], v[176:179], v[200:203], v[16:19]
	v_mfma_f32_16x16x32_bf16 v[4:7], v[168:171], v[210:213], v[4:7]
	v_mfma_f32_16x16x32_bf16 v[0:3], v[176:179], v[210:213], v[0:3]
	s_barrier
	s_add_i32 s58, 0, 0x18000
	s_add_i32 s59, 0, 0x1c000
	v_add_u32_e32 v160, s58, v146
	v_add_u32_e32 v176, s59, v146
	ds_read_b128 v[142:145], v160
	ds_read_b128 v[152:155], v160 offset:1024
	ds_read_b128 v[156:159], v160 offset:2048
	ds_read_b128 v[160:163], v160 offset:3072
	ds_read_b128 v[164:167], v176
	ds_read_b128 v[168:171], v176 offset:1024
	ds_read_b128 v[172:175], v176 offset:2048
	ds_read_b128 v[176:179], v176 offset:3072
	s_add_u32 s24, s24, 0x40000
	s_addc_u32 s25, s25, 0
	s_mov_b32 m0, s36
	v_lshl_add_u64 v[222:223], s[24:25], 0, v[128:129]
	ds_read_b128 v[180:183], v150 offset:32768
	ds_read_b128 v[184:187], v150 offset:33792
	ds_read_b128 v[188:191], v150 offset:34816
	ds_read_b128 v[192:195], v150 offset:35840
	ds_read_b128 v[196:199], v150 offset:36864
	ds_read_b128 v[200:203], v150 offset:37888
	ds_read_b128 v[206:209], v150 offset:38912
	ds_read_b128 v[210:213], v150 offset:39936
	global_load_lds_dwordx4 v[222:223], off
	v_lshl_add_u64 v[222:223], s[24:25], 0, v[132:133]
	s_mov_b32 m0, s37
	s_nop 0
	global_load_lds_dwordx4 v[222:223], off
	s_waitcnt vmcnt(8)
	s_waitcnt lgkmcnt(0)
	s_barrier
	s_waitcnt lgkmcnt(0)
	v_mfma_f32_16x16x32_bf16 v[124:127], v[142:145], v[180:183], v[124:127]
	v_mfma_f32_16x16x32_bf16 v[120:123], v[156:159], v[180:183], v[120:123]
	v_mfma_f32_16x16x32_bf16 v[108:111], v[142:145], v[188:191], v[108:111]
	v_mfma_f32_16x16x32_bf16 v[104:107], v[156:159], v[188:191], v[104:107]
	v_mfma_f32_16x16x32_bf16 v[92:95], v[142:145], v[196:199], v[92:95]
	v_mfma_f32_16x16x32_bf16 v[88:91], v[156:159], v[196:199], v[88:91]
	v_mfma_f32_16x16x32_bf16 v[76:79], v[142:145], v[206:209], v[76:79]
	v_mfma_f32_16x16x32_bf16 v[72:75], v[156:159], v[206:209], v[72:75]
	v_mfma_f32_16x16x32_bf16 v[124:127], v[152:155], v[184:187], v[124:127]
	v_mfma_f32_16x16x32_bf16 v[120:123], v[160:163], v[184:187], v[120:123]
	v_mfma_f32_16x16x32_bf16 v[108:111], v[152:155], v[192:195], v[108:111]
	v_mfma_f32_16x16x32_bf16 v[104:107], v[160:163], v[192:195], v[104:107]
	v_mfma_f32_16x16x32_bf16 v[92:95], v[152:155], v[200:203], v[92:95]
	v_mfma_f32_16x16x32_bf16 v[88:91], v[160:163], v[200:203], v[88:91]
	v_mfma_f32_16x16x32_bf16 v[76:79], v[152:155], v[210:213], v[76:79]
	v_mfma_f32_16x16x32_bf16 v[72:75], v[160:163], v[210:213], v[72:75]
	v_mfma_f32_16x16x32_bf16 v[116:119], v[164:167], v[180:183], v[116:119]
	v_mfma_f32_16x16x32_bf16 v[112:115], v[172:175], v[180:183], v[112:115]
	v_mfma_f32_16x16x32_bf16 v[100:103], v[164:167], v[188:191], v[100:103]
	v_mfma_f32_16x16x32_bf16 v[96:99], v[172:175], v[188:191], v[96:99]
	v_mfma_f32_16x16x32_bf16 v[84:87], v[164:167], v[196:199], v[84:87]
	v_mfma_f32_16x16x32_bf16 v[80:83], v[172:175], v[196:199], v[80:83]
	v_mfma_f32_16x16x32_bf16 v[68:71], v[164:167], v[206:209], v[68:71]
	v_mfma_f32_16x16x32_bf16 v[64:67], v[172:175], v[206:209], v[64:67]
	v_mfma_f32_16x16x32_bf16 v[116:119], v[168:171], v[184:187], v[116:119]
	v_mfma_f32_16x16x32_bf16 v[112:115], v[176:179], v[184:187], v[112:115]
	v_mfma_f32_16x16x32_bf16 v[100:103], v[168:171], v[192:195], v[100:103]
	v_mfma_f32_16x16x32_bf16 v[96:99], v[176:179], v[192:195], v[96:99]
	v_mfma_f32_16x16x32_bf16 v[84:87], v[168:171], v[200:203], v[84:87]
	v_mfma_f32_16x16x32_bf16 v[80:83], v[176:179], v[200:203], v[80:83]
	v_mfma_f32_16x16x32_bf16 v[68:71], v[168:171], v[210:213], v[68:71]
	v_mfma_f32_16x16x32_bf16 v[64:67], v[176:179], v[210:213], v[64:67]
	s_barrier
; #define PG8_STAGE(bufoff, gbase, voff) do { _Pragma("unroll") for (int _i = 0; _i < 2; ++_i) \
;         __builtin_amdgcn_global_load_lds((const unsigned*)((const char*)(gbase) + (voff)[_i]), (PG8_LAS unsigned*)(lds + (bufoff) + ldsw + _i * 8192), 16, 0, 0); } while (0)
; #define PG8_LDA(dst, b, h) do { _Pragma("unroll") for (int m = 0; m < 4; ++m) _Pragma("unroll") for (int k = 0; k < 2; ++k) dst[m][k] = *(const PG8_LAS bf16x8*)(lds + PG8_SA(b, h) + aoff + m * 2048 + k * 1024); } while (0)
; #define PG8_MMA(ai, bj, At, Bt) do { __builtin_amdgcn_s_setprio(1); _Pragma("unroll") for (int m = 0; m < 4; ++m) _Pragma("unroll") for (int n = 0; n < 2; ++n) _Pragma("unroll") for (int k = 0; k < 2; ++k) \
;         acc[ai][bj][m][n] = __builtin_amdgcn_mfma_f32_16x16x32_bf16(Bt[n][k], At[m][k], acc[ai][bj][m][n], 0, 0, 0); __builtin_amdgcn_s_setprio(0); } while (0)
; #define PG8_WAIT_V(n) asm volatile("s_waitcnt vmcnt(" #n ")" ::: "memory")
; #define PG8_WAIT_L(n) asm volatile("s_waitcnt lgkmcnt(" #n ")" ::: "memory")
; #define PG8_BAR __builtin_amdgcn_s_barrier()
; #define PG8_SCHED __builtin_amdgcn_sched_barrier(0)
; template <class Epi, class Sched, bool ALIGN_EPI = false, bool SP2 = false>
; __device__ __forceinline__ void gemm_phase(PG8_LAS unsigned char* lds, const Gemm g, const Sched& S, const Epi& E) {
;     ...
;             PG8_LDA(At, 1, 1); PG8_STAGE(PG8_SB(1, 0), b3, voffB); PG8_STAGE(PG8_SB(1, 1), b3 + hstep, voffB); PG8_STAGE(PG8_SA(1, 0), a3, voffA);
;             PG8_WAIT_V(8); PG8_WAIT_L(0); PG8_BAR; PG8_MMA(1, 0, At, B0); PG8_MMA(1, 1, At, B1); PG8_BAR; PG8_SCHED;
;     ...
;         if constexpr (ALIGN_EPI) { if (wr == 0) PG8_BAR; }
	s_add_i32 s24, s58, s31
	v_lshl_add_u64 v[214:215], v[214:215], 0, s[8:9]
	s_mov_b32 m0, s24
	ds_read_b128 v[180:183], v150 offset:49152
	ds_read_b128 v[184:187], v150 offset:50176
	ds_read_b128 v[188:191], v150 offset:51200
	ds_read_b128 v[192:195], v150 offset:52224
	ds_read_b128 v[196:199], v150 offset:53248
	ds_read_b128 v[200:203], v150 offset:54272
	ds_read_b128 v[206:209], v150 offset:55296
	ds_read_b128 v[210:213], v150 offset:56320
	global_load_lds_dwordx4 v[214:215], off
	s_add_i32 m0, s24, 0x2000
	s_add_u32 s2, s2, 0x40080
	v_lshl_add_u64 v[214:215], v[216:217], 0, s[8:9]
	s_addc_u32 s3, s3, 0
	s_add_i32 s24, s59, s31
	global_load_lds_dwordx4 v[214:215], off
	v_lshl_add_u64 v[214:215], s[2:3], 0, v[130:131]
	s_mov_b32 m0, s24
	s_nop 0
	global_load_lds_dwordx4 v[214:215], off
	v_lshl_add_u64 v[214:215], s[2:3], 0, v[134:135]
	s_add_i32 m0, s24, 0x2000
	s_nop 0
	global_load_lds_dwordx4 v[214:215], off
	v_lshl_add_u64 v[214:215], v[218:219], 0, s[8:9]
	s_mov_b32 m0, s39
	s_nop 0
	global_load_lds_dwordx4 v[214:215], off
	v_lshl_add_u64 v[214:215], v[220:221], 0, s[8:9]
	s_mov_b32 m0, s40
	s_nop 0
	global_load_lds_dwordx4 v[214:215], off
	s_waitcnt vmcnt(8)
	s_waitcnt lgkmcnt(0)
	s_barrier
	s_waitcnt lgkmcnt(0)
	v_mfma_f32_16x16x32_bf16 v[60:63], v[142:145], v[180:183], v[60:63]
	v_mfma_f32_16x16x32_bf16 v[56:59], v[156:159], v[180:183], v[56:59]
	v_mfma_f32_16x16x32_bf16 v[44:47], v[142:145], v[188:191], v[44:47]
	v_mfma_f32_16x16x32_bf16 v[40:43], v[156:159], v[188:191], v[40:43]
	v_mfma_f32_16x16x32_bf16 v[28:31], v[142:145], v[196:199], v[28:31]
	v_mfma_f32_16x16x32_bf16 v[24:27], v[156:159], v[196:199], v[24:27]
	v_mfma_f32_16x16x32_bf16 v[12:15], v[142:145], v[206:209], v[12:15]
	v_mfma_f32_16x16x32_bf16 v[8:11], v[156:159], v[206:209], v[8:11]
	v_mfma_f32_16x16x32_bf16 v[60:63], v[152:155], v[184:187], v[60:63]
	v_mfma_f32_16x16x32_bf16 v[56:59], v[160:163], v[184:187], v[56:59]
	v_mfma_f32_16x16x32_bf16 v[44:47], v[152:155], v[192:195], v[44:47]
	v_mfma_f32_16x16x32_bf16 v[40:43], v[160:163], v[192:195], v[40:43]
	v_mfma_f32_16x16x32_bf16 v[28:31], v[152:155], v[200:203], v[28:31]
	v_mfma_f32_16x16x32_bf16 v[24:27], v[160:163], v[200:203], v[24:27]
	v_mfma_f32_16x16x32_bf16 v[12:15], v[152:155], v[210:213], v[12:15]
	v_mfma_f32_16x16x32_bf16 v[8:11], v[160:163], v[210:213], v[8:11]
	v_mfma_f32_16x16x32_bf16 v[52:55], v[164:167], v[180:183], v[52:55]
	v_mfma_f32_16x16x32_bf16 v[48:51], v[172:175], v[180:183], v[48:51]
	v_mfma_f32_16x16x32_bf16 v[36:39], v[164:167], v[188:191], v[36:39]
	v_mfma_f32_16x16x32_bf16 v[32:35], v[172:175], v[188:191], v[32:35]
	v_mfma_f32_16x16x32_bf16 v[20:23], v[164:167], v[196:199], v[20:23]
	v_mfma_f32_16x16x32_bf16 v[16:19], v[172:175], v[196:199], v[16:19]
	v_mfma_f32_16x16x32_bf16 v[4:7], v[164:167], v[206:209], v[4:7]
	v_mfma_f32_16x16x32_bf16 v[0:3], v[172:175], v[206:209], v[0:3]
	v_mfma_f32_16x16x32_bf16 v[52:55], v[168:171], v[184:187], v[52:55]
	v_mfma_f32_16x16x32_bf16 v[48:51], v[176:179], v[184:187], v[48:51]
	v_mfma_f32_16x16x32_bf16 v[36:39], v[168:171], v[192:195], v[36:39]
	v_mfma_f32_16x16x32_bf16 v[32:35], v[176:179], v[192:195], v[32:35]
	v_mfma_f32_16x16x32_bf16 v[20:23], v[168:171], v[200:203], v[20:23]
	v_mfma_f32_16x16x32_bf16 v[16:19], v[176:179], v[200:203], v[16:19]
	v_mfma_f32_16x16x32_bf16 v[4:7], v[168:171], v[210:213], v[4:7]
	v_mfma_f32_16x16x32_bf16 v[0:3], v[176:179], v[210:213], v[0:3]
	s_barrier
	s_add_i32 s55, s55, 2
	s_add_u32 s22, s22, 0x100
	s_addc_u32 s23, s23, 0
	s_add_u32 s49, s49, 0x100
	s_addc_u32 s54, s54, 0
	s_cmp_gt_u32 s55, 13
	s_cbranch_scc0 .LBB0_349
	s_and_b64 vcc, exec, s[10:11]
	s_cbranch_vccz .LBB0_352
	s_barrier
